# SB cross-unit prefetch: next unit's K0/V0/Q loads issued at unit end before the output stores; unit-top wait vmcnt(8) so stores drain under next unit
# speedup vs baseline: 1.0027x; 1.0027x over previous
; #define LAS __attribute__((address_space(3)))
; __device__ __forceinline__ void p_attn_sb(const Params& P, LAS unsigned char* lds) {
;     ATT_COMMON_SETUP
;     LAS int* flags = (LAS int*)(lds + A_FL);
;     h16x8 uf[2], ones;
; #pragma unroll
;     for (int ks = 0; ks < 2; ++ks)
; #pragma unroll
;         for (int jj = 0; jj < 8; ++jj) { const int k = 16 * ks + 8 * (jj >> 2) + 4 * hh + (jj & 3); uf[ks][jj] = (k > r) ? (h16)1.0f : (h16)0.0f; }
; #pragma unroll
;     for (int jj = 0; jj < 8; ++jj) ones[jj] = (h16)1.0f;
;     for (int L = blockIdx.x; L < 4096; L += gridDim.x) {
;         const int qb = (L >> 8) & 7, bh = (L & 255) + 256 * (L >> 11), b = bh >> 4, h = bh & 15;
;         const size_t tokbase = (size_t)b * SEQ;
;         const h16* Kg = Kb + (size_t)bh * SEQ * DH; const h16* Vg = Vb + (size_t)bh * SEQ * DH;
;         const int t = 256 * qb + 32 * w + r;
;         const int nt = 4 * qb + 4;
;         __syncthreads();
;         if (tid < 16) flags[tid] = 0;
;         { const size_t go = (size_t)(64 * (nt - 1) + srow) * DH + sch * 8; const u32x4 k0 = *(const u32x4*)(Kg + go), v0 = *(const u32x4*)(Vg + go);
;           *(LAS u32x4*)(lds + A_K + srow * KP + sch * 16) = k0; *(LAS u32x4*)(lds + A_V + srow * KP + sch * 16) = v0; }
;         h16x8 qf[4];
;         { const h16* qp = Qb + (tokbase + t) * DM + h * DH + 8 * hh;
; #pragma unroll
;           for (int ks = 0; ks < 4; ++ks) qf[ks] = *(const h16x8*)(qp + 16 * ks); }
.LBB0_390:
	v_readlane_b32 s5, v255, 31
	s_or_b32 s5, s5, 3
	s_cmp_gt_i32 s68, s5
	s_cselect_b64 s[6:7], -1, 0
	s_cmp_ge_i32 s5, s69
	s_cselect_b64 s[8:9], -1, 0
	s_or_b64 s[6:7], s[6:7], s[8:9]
	v_writelane_b32 v255, s6, 33
	s_and_b64 vcc, exec, s[6:7]
	s_nop 0
	v_writelane_b32 v255, s7, 34
	s_cbranch_vccnz .LBB0_644
	s_getreg_b32 s5, hwreg(HW_REG_HW_ID, 0, 6)
	s_and_b32 s5, s5, 63
	s_lshl_b32 s5, s5, 2
	s_or_b32 s5, s5, 0x25000
	v_mov_b32_e32 v1, s5
	s_waitcnt vmcnt(0) lgkmcnt(0)
	ds_read_b32 v17, v1
	v_readlane_b32 s8, v255, 29
	v_readlane_b32 s9, v255, 30
	s_mov_b64 s[6:7], -1
	s_and_b64 vcc, exec, s[8:9]
	s_cbranch_vccz .LBB0_411
	v_mbcnt_lo_u32_b32 v1, -1, 0
	v_mbcnt_hi_u32_b32 v1, -1, v1
	s_waitcnt lgkmcnt(0)
	v_readfirstlane_b32 s5, v17
	v_readlane_b32 s6, v254, 20
	v_readlane_b32 s7, v254, 21
	v_lshl_add_u32 v1, s5, 6, v1
	s_andn2_b64 vcc, exec, s[6:7]
	v_readfirstlane_b32 s5, v1
	s_cbranch_vccnz .LBB0_410
	v_bfe_u32 v2, v1, 5, 1
	v_and_b32_e32 v163, 31, v1
	v_lshlrev_b32_e32 v162, 2, v2
	v_cmp_gt_u32_e32 vcc, v162, v163
	v_mov_b32_e32 v12, 0x3c00
	v_or_b32_e32 v6, 17, v162
	v_cndmask_b32_e32 v4, 0, v12, vcc
	v_cmp_lt_u32_e32 vcc, v162, v163
	v_or_b32_e32 v8, 19, v162
	v_or_b32_e32 v7, 24, v162
	v_cndmask_b32_e64 v5, v12, 0, vcc
	v_pack_b32_f16 v98, v4, v5
	v_or_b32_e32 v4, 3, v162
	v_or_b32_e32 v5, 2, v162
	v_cmp_gt_u32_e32 vcc, v4, v163
	v_or_b32_e32 v9, 26, v162
	v_or_b32_e32 v10, 25, v162
	v_cndmask_b32_e32 v4, 0, v12, vcc
	v_cmp_gt_u32_e32 vcc, v5, v163
	v_or_b32_e32 v11, 27, v162
	v_ashrrev_i32_e32 v165, 3, v1
	v_cndmask_b32_e32 v5, 0, v12, vcc
	v_pack_b32_f16 v99, v5, v4
	v_or_b32_e32 v4, 9, v162
	v_or_b32_e32 v5, 8, v162
	v_cmp_gt_u32_e32 vcc, v4, v163
	s_ashr_i32 s5, s5, 6
	s_movk_i32 s6, 0x90
	v_cndmask_b32_e32 v4, 0, v12, vcc
	v_cmp_gt_u32_e32 vcc, v5, v163
	v_and_b32_e32 v3, 63, v1
	v_cmp_gt_i32_e64 s[36:37], 16, v1
	v_cndmask_b32_e32 v5, 0, v12, vcc
	v_pack_b32_f16 v100, v5, v4
	v_or_b32_e32 v4, 11, v162
	v_or_b32_e32 v5, 10, v162
	v_cmp_gt_u32_e32 vcc, v4, v163
	s_lshl_b32 s10, s5, 5
	v_cmp_eq_u32_e64 s[38:39], 0, v3
	v_cndmask_b32_e32 v4, 0, v12, vcc
	v_cmp_gt_u32_e32 vcc, v5, v163
	v_lshlrev_b32_e32 v166, 1, v162
	s_mov_b32 s20, s2
	v_cndmask_b32_e32 v5, 0, v12, vcc
	v_pack_b32_f16 v101, v5, v4
	v_or_b32_e32 v4, 16, v162
	v_cmp_gt_u32_e32 vcc, v4, v163
	v_or_b32_e32 v5, 18, v162
	s_nop 0
	v_cndmask_b32_e32 v4, 0, v12, vcc
	v_cmp_gt_u32_e32 vcc, v6, v163
	s_nop 1
	v_cndmask_b32_e32 v6, 0, v12, vcc
	v_cmp_gt_u32_e32 vcc, v5, v163
	v_pack_b32_f16 v102, v4, v6
	v_lshlrev_b32_e32 v6, 2, v1
	v_cndmask_b32_e32 v5, 0, v12, vcc
	v_cmp_gt_u32_e32 vcc, v8, v163
	v_lshlrev_b32_e32 v4, 4, v2
	v_add_u32_e32 v174, 0, v6
	v_cndmask_b32_e32 v8, 0, v12, vcc
	v_cmp_gt_u32_e32 vcc, v7, v163
	v_pack_b32_f16 v103, v5, v8
	v_lshrrev_b32_e32 v5, 2, v1
	v_cndmask_b32_e32 v7, 0, v12, vcc
	v_cmp_gt_u32_e32 vcc, v9, v163
	v_and_or_b32 v5, v5, 3, v162
	v_and_b32_e32 v8, 7, v1
	v_cndmask_b32_e32 v9, 0, v12, vcc
	v_cmp_gt_u32_e32 vcc, v10, v163
	v_mul_u32_u24_e32 v5, 0x90, v5
	v_lshlrev_b32_e32 v2, 3, v2
	v_cndmask_b32_e32 v10, 0, v12, vcc
	v_cmp_gt_u32_e32 vcc, v11, v163
	v_pack_b32_f16 v104, v7, v10
	v_and_b32_e32 v7, 16, v1
	v_cndmask_b32_e32 v11, 0, v12, vcc
	v_and_or_b32 v7, v6, 12, v7
	v_pack_b32_f16 v105, v9, v11
	v_lshlrev_b32_e32 v7, 1, v7
	v_mul_u32_u24_e32 v9, 0x90, v163
	v_mul_lo_u32 v1, v165, s6
	v_lshlrev_b32_e32 v6, 4, v8
	s_lshl_b32 s6, s5, 2
	v_lshlrev_b32_e32 v164, 3, v8
	v_add3_u32 v175, 0, v1, v6
	v_add3_u32 v176, 0, v9, v4
	v_add3_u32 v177, 0, v5, v7
	s_add_i32 s11, s6, 0
	v_lshlrev_b32_e32 v168, 1, v2
	s_mov_b32 s81, 0
	s_branch .LBB0_395
.LBB0_394:
	s_add_i32 s80, s20, s70
	s_mov_b32 s81, 0
	s_cmpk_lt_i32 s80, 0x1000
	s_cbranch_scc0 .Lsbpf_none
	s_bfe_u32 s84, s80, 0x30008
	s_ashr_i32 s85, s80, 3
	s_lshl_b32 s90, s84, 8
	s_and_b32 s84, s80, 0xff
	s_and_b32 s85, s85, 0xffffff00
	s_or_b32 s84, s85, s84
	s_ashr_i32 s86, s84, 4
	s_ashr_i32 s85, s84, 31
	s_ashr_i32 s87, s86, 31
	s_lshl_b64 s[88:89], s[84:85], 18
	v_readlane_b32 s84, v254, 18
	s_add_u32 s84, s84, s88
	v_readlane_b32 s85, v254, 19
	v_add_u32_e32 v226, s90, v165
	s_addc_u32 s85, s85, s89
	v_readlane_b32 s91, v254, 16
	v_add_u32_e32 v226, 0xc0, v226
	s_add_u32 s88, s91, s88
	v_readlane_b32 s91, v254, 17
	v_ashrrev_i32_e32 v227, 31, v226
	s_addc_u32 s89, s91, s89
	s_add_i32 s91, s90, s10
	v_lshlrev_b64 v[226:227], 7, v[226:227]
	v_or_b32_e32 v230, s91, v163
	v_lshl_or_b32 v226, v164, 1, v226
	v_lshl_add_u64 v[228:229], s[84:85], 0, v[226:227]
	v_lshl_add_u64 v[226:227], s[88:89], 0, v[226:227]
	v_ashrrev_i32_e32 v231, 31, v230
	global_load_dwordx4 v[122:125], v[228:229], off
	global_load_dwordx4 v[126:129], v[226:227], off
	s_lshl_b64 s[86:87], s[86:87], 21
	v_lshlrev_b64 v[226:227], 10, v[230:231]
	s_lshl_b32 s94, s80, 6
	v_lshl_add_u64 v[226:227], v[226:227], 0, s[86:87]
	s_and_b32 s94, s94, 0x3c0
	v_lshl_add_u64 v[226:227], v[226:227], 1, s[96:97]
	s_lshl_b32 s92, s94, 1
	s_mov_b32 s93, 0
	v_mov_b32_e32 v229, 0
	v_mov_b32_e32 v228, v168
	v_lshl_add_u64 v[226:227], v[226:227], 0, s[92:93]
	v_lshl_add_u64 v[226:227], v[226:227], 0, v[228:229]
	global_load_dwordx4 v[106:109], v[226:227], off
	global_load_dwordx4 v[110:113], v[226:227], off offset:32
	global_load_dwordx4 v[114:117], v[226:227], off offset:64
	global_load_dwordx4 v[118:121], v[226:227], off offset:96
	s_mov_b32 s81, 1

; #define LAS __attribute__((address_space(3)))
; __device__ __forceinline__ void p_attn_sb(const Params& P, LAS unsigned char* lds) {
;     ...
;         __syncthreads();
;         if (tid < 16) flags[tid] = 0;
;         { const size_t go = (size_t)(64 * (nt - 1) + srow) * DH + sch * 8; const u32x4 k0 = *(const u32x4*)(Kg + go), v0 = *(const u32x4*)(Vg + go);
;           *(LAS u32x4*)(lds + A_K + srow * KP + sch * 16) = k0; *(LAS u32x4*)(lds + A_V + srow * KP + sch * 16) = v0; }
;         h16x8 qf[4];
;         { const h16* qp = Qb + (tokbase + t) * DM + h * DH + 8 * hh;
; #pragma unroll
;           for (int ks = 0; ks < 4; ++ks) qf[ks] = *(const h16x8*)(qp + 16 * ks); }
;         __syncthreads();
;         float carry = 0.f; bool wdone = false; f32x16 o[2];
; #pragma unroll
;         for (int i = 0; i < 16; ++i) { o[0][i] = 0.f; o[1][i] = 0.f; }
.LBB0_395:
	s_waitcnt vmcnt(8)
	s_barrier
	s_and_saveexec_b64 s[6:7], s[36:37]
	ds_write_b32 v174, v0 offset:40192
	s_or_b64 exec, exec, s[6:7]
	s_bfe_u32 s6, s20, 0x30008
	s_ashr_i32 s7, s20, 3
	s_lshl_b32 s25, s6, 8
	s_lshl_b32 s24, s6, 2
	s_and_b32 s6, s20, 0xff
	s_and_b32 s7, s7, 0xffffff00
	s_or_b32 s6, s7, s6
	s_ashr_i32 s14, s6, 4
	s_ashr_i32 s7, s6, 31
	s_ashr_i32 s15, s14, 31
	s_lshl_b64 s[8:9], s[6:7], 18
	v_readlane_b32 s6, v254, 18
	s_add_u32 s6, s6, s8
	v_readlane_b32 s7, v254, 19
	v_add_u32_e32 v1, s25, v165
	s_addc_u32 s7, s7, s9
	v_readlane_b32 s12, v254, 16
	v_add_u32_e32 v2, 0xc0, v1
	s_add_u32 s8, s12, s8
	v_readlane_b32 s12, v254, 17
	v_ashrrev_i32_e32 v3, 31, v2
	s_addc_u32 s9, s12, s9
	s_add_i32 s26, s25, s10
	v_lshlrev_b64 v[2:3], 7, v[2:3]
	v_or_b32_e32 v170, s26, v163
	v_lshl_or_b32 v2, v164, 1, v2
	v_lshl_add_u64 v[4:5], s[6:7], 0, v[2:3]
	v_lshl_add_u64 v[2:3], s[8:9], 0, v[2:3]
	v_ashrrev_i32_e32 v171, 31, v170
	s_cmp_lg_u32 s81, 0
	s_cbranch_scc1 .Lsbpf_a
	global_load_dwordx4 v[122:125], v[4:5], off
	global_load_dwordx4 v[126:129], v[2:3], off
.Lsbpf_a:
	s_lshl_b64 s[14:15], s[14:15], 21
	v_lshlrev_b64 v[2:3], 10, v[170:171]
	s_lshl_b32 s12, s20, 6
	v_lshl_add_u64 v[172:173], v[2:3], 0, s[14:15]
	s_and_b32 s27, s12, 0x3c0
	v_lshl_add_u64 v[2:3], v[172:173], 1, s[96:97]
	s_lshl_b32 s58, s27, 1
	v_lshl_add_u64 v[2:3], v[2:3], 0, s[58:59]
	v_mov_b32_e32 v169, v0
	v_lshl_add_u64 v[2:3], v[2:3], 0, v[168:169]
	s_cmp_lg_u32 s81, 0
	s_cbranch_scc1 .Lsbpf_b
	global_load_dwordx4 v[106:109], v[2:3], off
	global_load_dwordx4 v[110:113], v[2:3], off offset:32
	global_load_dwordx4 v[114:117], v[2:3], off offset:64
	global_load_dwordx4 v[118:121], v[2:3], off offset:96
.Lsbpf_b:
	v_mov_b32_e32 v14, v0
	v_mov_b32_e32 v15, v0
	v_mov_b32_e32 v1, v0
	v_mov_b32_e32 v2, v0
	v_mov_b32_e32 v3, v0
	v_mov_b32_e32 v4, v0
	v_mov_b32_e32 v5, v0
	v_mov_b32_e32 v6, v0
	v_mov_b32_e32 v7, v0
	v_mov_b32_e32 v8, v0
	v_mov_b32_e32 v9, v0
	v_mov_b32_e32 v10, v0
	v_mov_b32_e32 v11, v0
	v_mov_b32_e32 v12, v0
	v_mov_b32_e32 v13, v0
	v_mov_b64_e32 v[48:49], v[14:15]
	s_mov_b32 s28, 3
	s_mov_b32 s33, 1
	s_mov_b32 s29, 6
	s_add_i32 s40, s24, 4
	v_mov_b32_e32 v167, 0
	s_mov_b64 s[16:17], 0
	v_mov_b64_e32 v[46:47], v[12:13]
	v_mov_b64_e32 v[44:45], v[10:11]
	v_mov_b64_e32 v[42:43], v[8:9]
	v_mov_b64_e32 v[40:41], v[6:7]
	v_mov_b64_e32 v[38:39], v[4:5]
	v_mov_b64_e32 v[36:37], v[2:3]
	v_mov_b64_e32 v[34:35], v[0:1]
	s_waitcnt vmcnt(5)
	ds_write_b128 v175, v[122:125]
	s_waitcnt vmcnt(4)
	ds_write_b128 v175, v[126:129] offset:18432
	v_mov_b64_e32 v[32:33], v[14:15]
	v_mov_b64_e32 v[30:31], v[12:13]
	v_mov_b64_e32 v[28:29], v[10:11]
	v_mov_b64_e32 v[26:27], v[8:9]
	v_mov_b64_e32 v[24:25], v[6:7]
	v_mov_b64_e32 v[22:23], v[4:5]
	v_mov_b64_e32 v[20:21], v[2:3]
	v_mov_b64_e32 v[18:19], v[0:1]
	s_waitcnt lgkmcnt(0)
	s_barrier
	s_branch .LBB0_399
